# ret_out epilogue: all 16 gate loads and norm gains issued up front instead of per-round load/wait
# speedup vs baseline: 1.0107x; 1.0007x over previous
; #define LAS __attribute__((address_space(3)))
; DI unsigned pk2(float lo, float hi) { unsigned r; asm("v_cvt_pk_bf16_f32 %0, %1, %2" : "=v"(r) : "v"(lo), "v"(hi)); return r; }
; DI float bflo(unsigned u) { return __uint_as_float(u << 16); }
; DI float bfhi(unsigned u) { return __uint_as_float(u & 0xffff0000u); }
; DI float fsilu(float x) { return x * fsigmoid(x); }
; DI void ret_out_phase(int l, unsigned char* lds_g, LAS unsigned char* lds) {
;     ...
;         for (int nt = 0; nt < 8; ++nt) { const int i = 16 * nt + fr; float tot = 0.f;
; #pragma unroll
;             for (int ww = 0; ww < 8; ++ww) tot += *(const LAS float*)(lds + OT + (ww * 128 + i) * 4);
;             const float rinv = __builtin_amdgcn_rsqf(tot * (1.0f / 256.0f) + EPS);
; #pragma unroll
;             for (int m = 0; m < 2; ++m) { const int dv = h * 256 + 32 * w + 16 * m + 4 * fq;
;                 const u32x2 gz = *(const u32x2*)(Z + (row0 + i) * INW + ZC_RG + dv); const f32x4 gn = *(const f32x4*)(rn + dv);
;                 const float o0 = O[m][nt][0] * rinv * gn[0] * fsilu(bflo(gz.x)), o1 = O[m][nt][1] * rinv * gn[1] * fsilu(bfhi(gz.x));
;                 const float o2 = O[m][nt][2] * rinv * gn[2] * fsilu(bflo(gz.y)), o3 = O[m][nt][3] * rinv * gn[3] * fsilu(bfhi(gz.y));
;                 u32x2 o; o.x = pk2(o0, o1); o.y = pk2(o2, o3);
;                 *(u32x2*)(R + (row0 + i) * 1024 + dv) = o; }
;             asm volatile("" ::: "memory"); }
.LBB0_425:
	s_or_b64 exec, exec, s[54:55]
	v_or_b32_e32 v78, s52, v130
	v_mov_b64_e32 v[76:77], s[8:9]
	v_add_u32_e32 v74, s12, v133
	v_mad_u64_u32 v[72:73], s[22:23], v78, s78, v[76:77]
	s_mul_i32 s7, s53, 0x4c00
	v_ashrrev_i32_e32 v75, 31, v74
	v_add_u32_e32 v73, s7, v73
	v_lshl_add_u64 v[82:83], v[72:73], 0, s[28:29]
	v_lshlrev_b64 v[72:73], 1, v[74:75]
	v_lshl_add_u64 v[80:81], v[82:83], 0, v[72:73]
	s_waitcnt lgkmcnt(0)
	s_barrier
	v_lshl_add_u64 v[70:71], v[74:75], 2, s[50:51]
	global_load_dwordx4 v[200:203], v[70:71], off
	global_load_dwordx4 v[224:227], v[70:71], off offset:64
	global_load_dwordx2 v[100:101], v[80:81], off
	global_load_dwordx2 v[102:103], v[80:81], off offset:32
	s_mov_b32 s22, 0x4c000
	s_mov_b32 s23, 0
	v_lshl_add_u64 v[128:129], v[80:81], 0, s[22:23]
	global_load_dwordx2 v[104:105], v[128:129], off
	global_load_dwordx2 v[106:107], v[128:129], off offset:32
	s_mov_b32 s22, 0x98000
	s_mov_b32 s23, 0
	v_lshl_add_u64 v[128:129], v[80:81], 0, s[22:23]
	global_load_dwordx2 v[108:109], v[128:129], off
	global_load_dwordx2 v[110:111], v[128:129], off offset:32
	s_mov_b32 s22, 0xe4000
	s_mov_b32 s23, 0
	v_lshl_add_u64 v[128:129], v[80:81], 0, s[22:23]
	global_load_dwordx2 v[112:113], v[128:129], off
	global_load_dwordx2 v[114:115], v[128:129], off offset:32
	s_mov_b32 s22, 0x130000
	s_mov_b32 s23, 0
	v_lshl_add_u64 v[128:129], v[80:81], 0, s[22:23]
	global_load_dwordx2 v[116:117], v[128:129], off
	global_load_dwordx2 v[118:119], v[128:129], off offset:32
	s_mov_b32 s22, 0x17c000
	s_mov_b32 s23, 0
	v_lshl_add_u64 v[128:129], v[80:81], 0, s[22:23]
	global_load_dwordx2 v[120:121], v[128:129], off
	global_load_dwordx2 v[122:123], v[128:129], off offset:32
	s_mov_b32 s22, 0x1c8000
	s_mov_b32 s23, 0
	v_lshl_add_u64 v[128:129], v[80:81], 0, s[22:23]
	global_load_dwordx2 v[124:125], v[128:129], off
	global_load_dwordx2 v[126:127], v[128:129], off offset:32
	s_mov_b32 s22, 0x214000
	s_mov_b32 s23, 0
	v_lshl_add_u64 v[128:129], v[80:81], 0, s[22:23]
	global_load_dwordx2 v[220:221], v[128:129], off
	global_load_dwordx2 v[222:223], v[128:129], off offset:32
	v_add_u32_e32 v75, s58, v161
	ds_read2st64_b32 v[84:85], v75 offset1:2
	ds_read2st64_b32 v[86:87], v75 offset0:4 offset1:6
	ds_read2st64_b32 v[88:89], v75 offset0:8 offset1:10
	ds_read2st64_b32 v[90:91], v75 offset0:12 offset1:14
	v_mov_b32_e32 v79, s53
	s_waitcnt lgkmcnt(3)
	v_add_f32_e32 v84, 0, v84
	v_add_f32_e32 v84, v84, v85
	s_waitcnt lgkmcnt(2)
	v_add_f32_e32 v84, v84, v86
	v_add_f32_e32 v84, v84, v87
	s_waitcnt lgkmcnt(1)
	v_add_f32_e32 v84, v84, v88
	v_add_f32_e32 v84, v84, v89
	s_waitcnt lgkmcnt(0)
	v_add_f32_e32 v84, v84, v90
	v_add_f32_e32 v84, v84, v91
	v_fmamk_f32 v84, v84, 0x3b800000, v243
	v_rsq_f32_e32 v96, v84
	v_lshlrev_b64 v[78:79], 11, v[78:79]
	v_or_b32_e32 v74, 16, v74
	v_lshl_add_u64 v[78:79], s[48:49], 0, v[78:79]
	v_mul_f32_e32 v84, v2, v96
	v_mul_f32_e32 v86, v3, v96
	v_ashrrev_i32_e32 v75, 31, v74
	v_mul_f32_e32 v88, v4, v96
	v_mul_f32_e32 v90, v5, v96
	v_lshl_add_u64 v[78:79], v[78:79], 0, v[72:73]
	v_lshlrev_b64 v[74:75], 1, v[74:75]
	v_lshl_add_u64 v[82:83], v[82:83], 0, v[74:75]
	s_add_i32 s6, s6, s14
	s_cmpk_lt_i32 s6, 0x200
	s_waitcnt vmcnt(15)
	v_mov_b32_e32 v80, v100
	v_mov_b32_e32 v81, v101
	v_lshlrev_b32_e32 v85, 16, v80
	v_and_b32_e32 v87, 0xffff0000, v80
	v_mov_b32_e32 v66, v200
	v_mov_b32_e32 v67, v201
	v_mov_b32_e32 v68, v202
	v_mov_b32_e32 v69, v203
	v_mov_b32_e32 v92, v67
	v_mov_b32_e32 v94, v69
	v_lshlrev_b32_e32 v89, 16, v81
	v_and_b32_e32 v91, 0xffff0000, v81
	v_mul_f32_e32 v67, 0xbfb8aa3b, v85
	v_mul_f32_e32 v69, 0xbfb8aa3b, v87
	v_mul_f32_e32 v80, 0xbfb8aa3b, v89
	v_mul_f32_e32 v81, 0xbfb8aa3b, v91
	v_exp_f32_e32 v67, v67
	v_exp_f32_e32 v69, v69
	v_exp_f32_e32 v80, v80
	v_exp_f32_e32 v81, v81
	v_add_f32_e32 v67, 1.0, v67
	v_add_f32_e32 v69, 1.0, v69
	v_add_f32_e32 v80, 1.0, v80
	v_add_f32_e32 v81, 1.0, v81
	v_rcp_f32_e32 v67, v67
	v_rcp_f32_e32 v93, v69
	v_rcp_f32_e32 v69, v80
	v_rcp_f32_e32 v95, v81
	v_pk_mul_f32 v[66:67], v[66:67], v[84:85]
	v_pk_mul_f32 v[80:81], v[92:93], v[86:87]
	v_pk_mul_f32 v[68:69], v[68:69], v[88:89]
	v_pk_mul_f32 v[84:85], v[94:95], v[90:91]
	v_mul_f32_e32 v66, v66, v67
	v_mul_f32_e32 v67, v80, v81
	v_mul_f32_e32 v68, v68, v69
	v_mul_f32_e32 v69, v84, v85
	v_cvt_pk_bf16_f32 v66, v66, v67
	v_cvt_pk_bf16_f32 v67, v68, v69
	global_store_dwordx2 v[78:79], v[66:67], off
	s_nop 0
	v_mul_f32_e32 v88, v34, v96
	v_mul_f32_e32 v90, v35, v96
	v_mul_f32_e32 v92, v36, v96
	v_mul_f32_e32 v94, v37, v96
	v_or_b32_e32 v84, s52, v160
	v_mad_u64_u32 v[80:81], s[22:23], v84, s78, v[76:77]
	v_add_u32_e32 v81, s7, v81
	v_lshl_add_u64 v[80:81], v[80:81], 0, s[28:29]
	v_lshl_add_u64 v[86:87], v[80:81], 0, v[72:73]
	v_lshl_add_u64 v[80:81], v[80:81], 0, v[74:75]
	s_waitcnt vmcnt(15)
	v_mov_b32_e32 v82, v102
	v_mov_b32_e32 v83, v103
	v_lshlrev_b32_e32 v97, 16, v82
	v_mov_b32_e32 v66, v224
	v_mov_b32_e32 v67, v225
	v_mov_b32_e32 v68, v226
	v_mov_b32_e32 v69, v227
	v_mov_b32_e32 v98, v67
	v_lshlrev_b32_e32 v67, 16, v83
	v_and_b32_e32 v99, 0xffff0000, v82
	v_and_b32_e32 v83, 0xffff0000, v83
	v_mul_f32_e32 v85, 0xbfb8aa3b, v67
	v_mov_b32_e32 v96, v66
	v_mov_b32_e32 v66, v68
	v_mov_b32_e32 v82, v69
	v_mul_f32_e32 v68, 0xbfb8aa3b, v97
	v_mul_f32_e32 v69, 0xbfb8aa3b, v99
	v_mul_f32_e32 v89, 0xbfb8aa3b, v83
	v_exp_f32_e32 v85, v85
	v_exp_f32_e32 v68, v68
	v_exp_f32_e32 v69, v69
	v_exp_f32_e32 v89, v89
	v_add_f32_e32 v85, 1.0, v85
	v_add_f32_e32 v68, 1.0, v68
	v_add_f32_e32 v69, 1.0, v69
	v_add_f32_e32 v95, 1.0, v89
	v_rcp_f32_e32 v93, v85
	v_rcp_f32_e32 v89, v68
	v_rcp_f32_e32 v91, v69
	v_rcp_f32_e32 v95, v95
	v_pk_mul_f32 v[66:67], v[92:93], v[66:67]
	v_pk_mul_f32 v[68:69], v[88:89], v[96:97]
	v_pk_mul_f32 v[88:89], v[90:91], v[98:99]
	v_pk_mul_f32 v[82:83], v[94:95], v[82:83]
	v_mul_f32_e32 v67, v66, v67
	v_mul_f32_e32 v68, v68, v69
	v_mul_f32_e32 v69, v88, v89
	v_mul_f32_e32 v82, v82, v83
	v_cvt_pk_bf16_f32 v66, v68, v69
	v_cvt_pk_bf16_f32 v67, v67, v82
	global_store_dwordx2 v[78:79], v[66:67], off offset:32
	ds_read2st64_b32 v[78:79], v212 offset1:2
	v_mov_b32_e32 v85, s53
	v_lshlrev_b64 v[86:87], 11, v[84:85]
	ds_read2st64_b32 v[84:85], v212 offset0:4 offset1:6
	ds_read2st64_b32 v[88:89], v212 offset0:8 offset1:10
	ds_read2st64_b32 v[90:91], v212 offset0:12 offset1:14
	s_waitcnt lgkmcnt(3)
; #define LAS __attribute__((address_space(3)))
; DI unsigned pk2(float lo, float hi) { unsigned r; asm("v_cvt_pk_bf16_f32 %0, %1, %2" : "=v"(r) : "v"(lo), "v"(hi)); return r; }
; DI float bflo(unsigned u) { return __uint_as_float(u << 16); }
; DI float bfhi(unsigned u) { return __uint_as_float(u & 0xffff0000u); }
; DI float fsilu(float x) { return x * fsigmoid(x); }
; DI void ret_out_phase(int l, unsigned char* lds_g, LAS unsigned char* lds) {
;     ...
;         for (int nt = 0; nt < 8; ++nt) { const int i = 16 * nt + fr; float tot = 0.f;
; #pragma unroll
;             for (int ww = 0; ww < 8; ++ww) tot += *(const LAS float*)(lds + OT + (ww * 128 + i) * 4);
;             const float rinv = __builtin_amdgcn_rsqf(tot * (1.0f / 256.0f) + EPS);
; #pragma unroll
;             for (int m = 0; m < 2; ++m) { const int dv = h * 256 + 32 * w + 16 * m + 4 * fq;
;                 const u32x2 gz = *(const u32x2*)(Z + (row0 + i) * INW + ZC_RG + dv); const f32x4 gn = *(const f32x4*)(rn + dv);
;                 const float o0 = O[m][nt][0] * rinv * gn[0] * fsilu(bflo(gz.x)), o1 = O[m][nt][1] * rinv * gn[1] * fsilu(bfhi(gz.x));
;                 const float o2 = O[m][nt][2] * rinv * gn[2] * fsilu(bflo(gz.y)), o3 = O[m][nt][3] * rinv * gn[3] * fsilu(bfhi(gz.y));
;                 u32x2 o; o.x = pk2(o0, o1); o.y = pk2(o2, o3);
;                 *(u32x2*)(R + (row0 + i) * 1024 + dv) = o; }
;             asm volatile("" ::: "memory"); }
	v_add_f32_e32 v78, 0, v78
	v_add_f32_e32 v78, v78, v79
	s_waitcnt lgkmcnt(2)
	v_add_f32_e32 v78, v78, v84
	v_add_f32_e32 v78, v78, v85
	s_waitcnt lgkmcnt(1)
	v_add_f32_e32 v78, v78, v88
	v_add_f32_e32 v78, v78, v89
	s_waitcnt lgkmcnt(0)
	v_add_f32_e32 v78, v78, v90
	v_add_f32_e32 v78, v78, v91
	v_fmamk_f32 v78, v78, 0x3b800000, v243
	v_rsq_f32_e32 v84, v78
	v_lshl_add_u64 v[78:79], s[48:49], 0, v[86:87]
	v_lshl_add_u64 v[78:79], v[78:79], 0, v[72:73]
	v_mul_f32_e32 v86, v6, v84
	v_mul_f32_e32 v88, v7, v84
	v_mul_f32_e32 v90, v8, v84
	v_mul_f32_e32 v92, v9, v84
	s_waitcnt vmcnt(15)
	v_mov_b32_e32 v82, v104
	v_mov_b32_e32 v83, v105
	v_lshlrev_b32_e32 v87, 16, v82
	v_and_b32_e32 v89, 0xffff0000, v82
	v_mov_b32_e32 v66, v200
	v_mov_b32_e32 v67, v201
	v_mov_b32_e32 v68, v202
	v_mov_b32_e32 v69, v203
	v_mov_b32_e32 v82, v67
	v_lshlrev_b32_e32 v91, 16, v83
	v_and_b32_e32 v93, 0xffff0000, v83
	v_mov_b32_e32 v94, v69
	v_mul_f32_e32 v67, 0xbfb8aa3b, v87
	v_mul_f32_e32 v69, 0xbfb8aa3b, v89
	v_mul_f32_e32 v83, 0xbfb8aa3b, v91
	v_mul_f32_e32 v85, 0xbfb8aa3b, v93
	v_exp_f32_e32 v67, v67
	v_exp_f32_e32 v69, v69
	v_exp_f32_e32 v83, v83
	v_exp_f32_e32 v85, v85
	v_add_f32_e32 v67, 1.0, v67
	v_add_f32_e32 v69, 1.0, v69
	v_add_f32_e32 v95, 1.0, v83
	v_add_f32_e32 v85, 1.0, v85
	v_rcp_f32_e32 v67, v67
	v_rcp_f32_e32 v83, v69
	v_rcp_f32_e32 v69, v95
	v_rcp_f32_e32 v95, v85
	v_pk_mul_f32 v[66:67], v[66:67], v[86:87]
	v_pk_mul_f32 v[82:83], v[82:83], v[88:89]
	v_pk_mul_f32 v[68:69], v[68:69], v[90:91]
	v_pk_mul_f32 v[86:87], v[94:95], v[92:93]
	v_mul_f32_e32 v66, v66, v67
	v_mul_f32_e32 v67, v82, v83
	v_mul_f32_e32 v68, v68, v69
	v_mul_f32_e32 v69, v86, v87
	v_cvt_pk_bf16_f32 v66, v66, v67
	v_cvt_pk_bf16_f32 v67, v68, v69
	global_store_dwordx2 v[78:79], v[66:67], off
	s_nop 0
	v_or_b32_e32 v86, s52, v162
	v_mul_f32_e32 v94, v40, v84
	v_mad_u64_u32 v[80:81], s[22:23], v86, s78, v[76:77]
	v_mul_f32_e32 v90, v38, v84
	v_mul_f32_e32 v92, v39, v84
	v_mul_f32_e32 v84, v41, v84
	v_add_u32_e32 v81, s7, v81
	v_lshl_add_u64 v[80:81], v[80:81], 0, s[28:29]
	v_lshl_add_u64 v[88:89], v[80:81], 0, v[72:73]
	v_lshl_add_u64 v[80:81], v[80:81], 0, v[74:75]
	s_waitcnt vmcnt(15)
	v_mov_b32_e32 v82, v106
	v_mov_b32_e32 v83, v107
	v_lshlrev_b32_e32 v97, 16, v82
	v_mov_b32_e32 v66, v224
	v_mov_b32_e32 v67, v225
	v_mov_b32_e32 v68, v226
	v_mov_b32_e32 v69, v227
	v_mov_b32_e32 v98, v67
	v_lshlrev_b32_e32 v67, 16, v83
	v_and_b32_e32 v99, 0xffff0000, v82
	v_and_b32_e32 v83, 0xffff0000, v83
	v_mul_f32_e32 v85, 0xbfb8aa3b, v67
	v_mov_b32_e32 v96, v66
	v_mov_b32_e32 v66, v68
	v_mov_b32_e32 v82, v69
	v_mul_f32_e32 v68, 0xbfb8aa3b, v97
	v_mul_f32_e32 v69, 0xbfb8aa3b, v99
	v_mul_f32_e32 v87, 0xbfb8aa3b, v83
	v_exp_f32_e32 v85, v85
	v_exp_f32_e32 v68, v68
	v_exp_f32_e32 v69, v69
	v_exp_f32_e32 v87, v87
	v_add_f32_e32 v85, 1.0, v85
	v_add_f32_e32 v68, 1.0, v68
	v_add_f32_e32 v69, 1.0, v69
	v_add_f32_e32 v87, 1.0, v87
	v_rcp_f32_e32 v95, v85
	v_rcp_f32_e32 v91, v68
	v_rcp_f32_e32 v93, v69
	v_rcp_f32_e32 v85, v87
	v_pk_mul_f32 v[66:67], v[94:95], v[66:67]
	v_pk_mul_f32 v[68:69], v[90:91], v[96:97]
	v_pk_mul_f32 v[90:91], v[92:93], v[98:99]
	v_pk_mul_f32 v[82:83], v[84:85], v[82:83]
	v_mul_f32_e32 v67, v66, v67
	v_mul_f32_e32 v68, v68, v69
	v_mul_f32_e32 v69, v90, v91
	v_mul_f32_e32 v82, v82, v83
	v_cvt_pk_bf16_f32 v66, v68, v69
	v_cvt_pk_bf16_f32 v67, v67, v82
	global_store_dwordx2 v[78:79], v[66:67], off offset:32
	ds_read2st64_b32 v[78:79], v213 offset1:2
	ds_read2st64_b32 v[84:85], v213 offset0:4 offset1:6
	ds_read2st64_b32 v[88:89], v213 offset0:8 offset1:10
	ds_read2st64_b32 v[90:91], v213 offset0:12 offset1:14
	v_mov_b32_e32 v87, s53
	v_lshlrev_b64 v[86:87], 11, v[86:87]
	s_waitcnt lgkmcnt(3)
	v_add_f32_e32 v78, 0, v78
	v_add_f32_e32 v78, v78, v79
	s_waitcnt lgkmcnt(2)
	v_add_f32_e32 v78, v78, v84
	v_add_f32_e32 v78, v78, v85
	s_waitcnt lgkmcnt(1)
	v_add_f32_e32 v78, v78, v88
	v_add_f32_e32 v78, v78, v89
	s_waitcnt lgkmcnt(0)
	v_add_f32_e32 v78, v78, v90
	v_add_f32_e32 v78, v78, v91
	v_fmamk_f32 v78, v78, 0x3b800000, v243
	v_rsq_f32_e32 v84, v78
	v_lshl_add_u64 v[78:79], s[48:49], 0, v[86:87]
	v_lshl_add_u64 v[78:79], v[78:79], 0, v[72:73]
	v_mul_f32_e32 v86, v10, v84
	v_mul_f32_e32 v88, v11, v84
	v_mul_f32_e32 v90, v12, v84
	v_mul_f32_e32 v92, v13, v84
	s_waitcnt vmcnt(15)
	v_mov_b32_e32 v82, v108
	v_mov_b32_e32 v83, v109
	v_lshlrev_b32_e32 v87, 16, v82
	v_and_b32_e32 v89, 0xffff0000, v82
	v_mov_b32_e32 v66, v200
	v_mov_b32_e32 v67, v201
	v_mov_b32_e32 v68, v202
	v_mov_b32_e32 v69, v203
	v_mov_b32_e32 v82, v67
	v_lshlrev_b32_e32 v91, 16, v83
	v_and_b32_e32 v93, 0xffff0000, v83
	v_mov_b32_e32 v94, v69
	v_mul_f32_e32 v67, 0xbfb8aa3b, v87
	v_mul_f32_e32 v69, 0xbfb8aa3b, v89
	v_mul_f32_e32 v83, 0xbfb8aa3b, v91
	v_mul_f32_e32 v85, 0xbfb8aa3b, v93
	v_exp_f32_e32 v67, v67
	v_exp_f32_e32 v69, v69
	v_exp_f32_e32 v83, v83
	v_exp_f32_e32 v85, v85
	v_add_f32_e32 v67, 1.0, v67
	v_add_f32_e32 v69, 1.0, v69
	v_add_f32_e32 v95, 1.0, v83
	v_add_f32_e32 v85, 1.0, v85
	v_rcp_f32_e32 v67, v67
	v_rcp_f32_e32 v83, v69
	v_rcp_f32_e32 v69, v95
	v_rcp_f32_e32 v95, v85
	v_pk_mul_f32 v[66:67], v[66:67], v[86:87]
	v_pk_mul_f32 v[82:83], v[82:83], v[88:89]
	v_pk_mul_f32 v[68:69], v[68:69], v[90:91]
	v_pk_mul_f32 v[86:87], v[94:95], v[92:93]
	v_mul_f32_e32 v66, v66, v67
	v_mul_f32_e32 v67, v82, v83
	v_mul_f32_e32 v68, v68, v69
	v_mul_f32_e32 v69, v86, v87
	v_cvt_pk_bf16_f32 v66, v66, v67
	v_cvt_pk_bf16_f32 v67, v68, v69
	global_store_dwordx2 v[78:79], v[66:67], off
	s_nop 0
	v_or_b32_e32 v86, s52, v164
	v_mul_f32_e32 v94, v44, v84
	v_mad_u64_u32 v[80:81], s[22:23], v86, s78, v[76:77]
	v_mul_f32_e32 v90, v42, v84
	v_mul_f32_e32 v92, v43, v84
	v_mul_f32_e32 v84, v45, v84
	v_add_u32_e32 v81, s7, v81
	v_lshl_add_u64 v[80:81], v[80:81], 0, s[28:29]
	v_lshl_add_u64 v[88:89], v[80:81], 0, v[72:73]
	v_lshl_add_u64 v[80:81], v[80:81], 0, v[74:75]
	s_waitcnt vmcnt(15)
; #define LAS __attribute__((address_space(3)))
; DI unsigned pk2(float lo, float hi) { unsigned r; asm("v_cvt_pk_bf16_f32 %0, %1, %2" : "=v"(r) : "v"(lo), "v"(hi)); return r; }
; DI float bflo(unsigned u) { return __uint_as_float(u << 16); }
; DI float bfhi(unsigned u) { return __uint_as_float(u & 0xffff0000u); }
; DI float fsilu(float x) { return x * fsigmoid(x); }
; DI void ret_out_phase(int l, unsigned char* lds_g, LAS unsigned char* lds) {
;     ...
;         for (int nt = 0; nt < 8; ++nt) { const int i = 16 * nt + fr; float tot = 0.f;
; #pragma unroll
;             for (int ww = 0; ww < 8; ++ww) tot += *(const LAS float*)(lds + OT + (ww * 128 + i) * 4);
;             const float rinv = __builtin_amdgcn_rsqf(tot * (1.0f / 256.0f) + EPS);
; #pragma unroll
;             for (int m = 0; m < 2; ++m) { const int dv = h * 256 + 32 * w + 16 * m + 4 * fq;
;                 const u32x2 gz = *(const u32x2*)(Z + (row0 + i) * INW + ZC_RG + dv); const f32x4 gn = *(const f32x4*)(rn + dv);
;                 const float o0 = O[m][nt][0] * rinv * gn[0] * fsilu(bflo(gz.x)), o1 = O[m][nt][1] * rinv * gn[1] * fsilu(bfhi(gz.x));
;                 const float o2 = O[m][nt][2] * rinv * gn[2] * fsilu(bflo(gz.y)), o3 = O[m][nt][3] * rinv * gn[3] * fsilu(bfhi(gz.y));
;                 u32x2 o; o.x = pk2(o0, o1); o.y = pk2(o2, o3);
;                 *(u32x2*)(R + (row0 + i) * 1024 + dv) = o; }
;             asm volatile("" ::: "memory"); }
	v_mov_b32_e32 v82, v110
	v_mov_b32_e32 v83, v111
	v_lshlrev_b32_e32 v97, 16, v82
	v_mov_b32_e32 v66, v224
	v_mov_b32_e32 v67, v225
	v_mov_b32_e32 v68, v226
	v_mov_b32_e32 v69, v227
	v_mov_b32_e32 v98, v67
	v_lshlrev_b32_e32 v67, 16, v83
	v_and_b32_e32 v99, 0xffff0000, v82
	v_and_b32_e32 v83, 0xffff0000, v83
	v_mul_f32_e32 v85, 0xbfb8aa3b, v67
	v_mov_b32_e32 v96, v66
	v_mov_b32_e32 v66, v68
	v_mov_b32_e32 v82, v69
	v_mul_f32_e32 v68, 0xbfb8aa3b, v97
	v_mul_f32_e32 v69, 0xbfb8aa3b, v99
	v_mul_f32_e32 v87, 0xbfb8aa3b, v83
	v_exp_f32_e32 v85, v85
	v_exp_f32_e32 v68, v68
	v_exp_f32_e32 v69, v69
	v_exp_f32_e32 v87, v87
	v_add_f32_e32 v85, 1.0, v85
	v_add_f32_e32 v68, 1.0, v68
	v_add_f32_e32 v69, 1.0, v69
	v_add_f32_e32 v87, 1.0, v87
	v_rcp_f32_e32 v95, v85
	v_rcp_f32_e32 v91, v68
	v_rcp_f32_e32 v93, v69
	v_rcp_f32_e32 v85, v87
	v_pk_mul_f32 v[66:67], v[94:95], v[66:67]
	v_pk_mul_f32 v[68:69], v[90:91], v[96:97]
	v_pk_mul_f32 v[90:91], v[92:93], v[98:99]
	v_pk_mul_f32 v[82:83], v[84:85], v[82:83]
	v_mul_f32_e32 v67, v66, v67
	v_mul_f32_e32 v68, v68, v69
	v_mul_f32_e32 v69, v90, v91
	v_mul_f32_e32 v82, v82, v83
	v_cvt_pk_bf16_f32 v66, v68, v69
	v_cvt_pk_bf16_f32 v67, v67, v82
	global_store_dwordx2 v[78:79], v[66:67], off offset:32
	ds_read2st64_b32 v[78:79], v214 offset1:2
	ds_read2st64_b32 v[84:85], v214 offset0:4 offset1:6
	ds_read2st64_b32 v[88:89], v214 offset0:8 offset1:10
	ds_read2st64_b32 v[90:91], v214 offset0:12 offset1:14
	v_mov_b32_e32 v87, s53
	v_lshlrev_b64 v[86:87], 11, v[86:87]
	s_waitcnt lgkmcnt(3)
	v_add_f32_e32 v78, 0, v78
	v_add_f32_e32 v78, v78, v79
	s_waitcnt lgkmcnt(2)
	v_add_f32_e32 v78, v78, v84
	v_add_f32_e32 v78, v78, v85
	s_waitcnt lgkmcnt(1)
	v_add_f32_e32 v78, v78, v88
	v_add_f32_e32 v78, v78, v89
	s_waitcnt lgkmcnt(0)
	v_add_f32_e32 v78, v78, v90
	v_add_f32_e32 v78, v78, v91
	v_fmamk_f32 v78, v78, 0x3b800000, v243
	v_rsq_f32_e32 v84, v78
	v_lshl_add_u64 v[78:79], s[48:49], 0, v[86:87]
	v_lshl_add_u64 v[78:79], v[78:79], 0, v[72:73]
	v_mul_f32_e32 v86, v14, v84
	v_mul_f32_e32 v88, v15, v84
	v_mul_f32_e32 v90, v16, v84
	v_mul_f32_e32 v92, v17, v84
	s_waitcnt vmcnt(15)
	v_mov_b32_e32 v82, v112
	v_mov_b32_e32 v83, v113
	v_lshlrev_b32_e32 v87, 16, v82
	v_and_b32_e32 v89, 0xffff0000, v82
	v_mov_b32_e32 v66, v200
	v_mov_b32_e32 v67, v201
	v_mov_b32_e32 v68, v202
	v_mov_b32_e32 v69, v203
	v_mov_b32_e32 v82, v67
	v_lshlrev_b32_e32 v91, 16, v83
	v_and_b32_e32 v93, 0xffff0000, v83
	v_mov_b32_e32 v94, v69
	v_mul_f32_e32 v67, 0xbfb8aa3b, v87
	v_mul_f32_e32 v69, 0xbfb8aa3b, v89
	v_mul_f32_e32 v83, 0xbfb8aa3b, v91
	v_mul_f32_e32 v85, 0xbfb8aa3b, v93
	v_exp_f32_e32 v67, v67
	v_exp_f32_e32 v69, v69
	v_exp_f32_e32 v83, v83
	v_exp_f32_e32 v85, v85
	v_add_f32_e32 v67, 1.0, v67
	v_add_f32_e32 v69, 1.0, v69
	v_add_f32_e32 v95, 1.0, v83
	v_add_f32_e32 v85, 1.0, v85
	v_rcp_f32_e32 v67, v67
	v_rcp_f32_e32 v83, v69
	v_rcp_f32_e32 v69, v95
	v_rcp_f32_e32 v95, v85
	v_pk_mul_f32 v[66:67], v[66:67], v[86:87]
	v_pk_mul_f32 v[82:83], v[82:83], v[88:89]
	v_pk_mul_f32 v[68:69], v[68:69], v[90:91]
	v_pk_mul_f32 v[86:87], v[94:95], v[92:93]
	v_mul_f32_e32 v66, v66, v67
	v_mul_f32_e32 v67, v82, v83
	v_mul_f32_e32 v68, v68, v69
	v_mul_f32_e32 v69, v86, v87
	v_cvt_pk_bf16_f32 v66, v66, v67
	v_cvt_pk_bf16_f32 v67, v68, v69
	global_store_dwordx2 v[78:79], v[66:67], off
	s_nop 0
	v_or_b32_e32 v86, s52, v166
	v_mul_f32_e32 v94, v48, v84
	v_mad_u64_u32 v[80:81], s[22:23], v86, s78, v[76:77]
	v_mul_f32_e32 v90, v46, v84
	v_mul_f32_e32 v92, v47, v84
	v_mul_f32_e32 v84, v49, v84
	v_add_u32_e32 v81, s7, v81
	v_lshl_add_u64 v[80:81], v[80:81], 0, s[28:29]
	v_lshl_add_u64 v[88:89], v[80:81], 0, v[72:73]
	v_lshl_add_u64 v[80:81], v[80:81], 0, v[74:75]
	s_waitcnt vmcnt(15)
	v_mov_b32_e32 v82, v114
	v_mov_b32_e32 v83, v115
	v_lshlrev_b32_e32 v97, 16, v82
	v_mov_b32_e32 v66, v224
	v_mov_b32_e32 v67, v225
	v_mov_b32_e32 v68, v226
	v_mov_b32_e32 v69, v227
	v_mov_b32_e32 v98, v67
	v_lshlrev_b32_e32 v67, 16, v83
	v_and_b32_e32 v99, 0xffff0000, v82
	v_and_b32_e32 v83, 0xffff0000, v83
	v_mul_f32_e32 v85, 0xbfb8aa3b, v67
	v_mov_b32_e32 v96, v66
	v_mov_b32_e32 v66, v68
	v_mov_b32_e32 v82, v69
	v_mul_f32_e32 v68, 0xbfb8aa3b, v97
	v_mul_f32_e32 v69, 0xbfb8aa3b, v99
	v_mul_f32_e32 v87, 0xbfb8aa3b, v83
	v_exp_f32_e32 v85, v85
	v_exp_f32_e32 v68, v68
	v_exp_f32_e32 v69, v69
	v_exp_f32_e32 v87, v87
	v_add_f32_e32 v85, 1.0, v85
	v_add_f32_e32 v68, 1.0, v68
	v_add_f32_e32 v69, 1.0, v69
	v_add_f32_e32 v87, 1.0, v87
	v_rcp_f32_e32 v95, v85
	v_rcp_f32_e32 v91, v68
	v_rcp_f32_e32 v93, v69
	v_rcp_f32_e32 v85, v87
	v_pk_mul_f32 v[66:67], v[94:95], v[66:67]
	v_pk_mul_f32 v[68:69], v[90:91], v[96:97]
	v_pk_mul_f32 v[90:91], v[92:93], v[98:99]
	v_pk_mul_f32 v[82:83], v[84:85], v[82:83]
	v_mul_f32_e32 v67, v66, v67
	v_mul_f32_e32 v68, v68, v69
	v_mul_f32_e32 v69, v90, v91
	v_mul_f32_e32 v82, v82, v83
	v_cvt_pk_bf16_f32 v66, v68, v69
	v_cvt_pk_bf16_f32 v67, v67, v82
	global_store_dwordx2 v[78:79], v[66:67], off offset:32
	ds_read2st64_b32 v[78:79], v215 offset1:2
	ds_read2st64_b32 v[84:85], v215 offset0:4 offset1:6
	ds_read2st64_b32 v[88:89], v215 offset0:8 offset1:10
	ds_read2st64_b32 v[90:91], v215 offset0:12 offset1:14
	v_mov_b32_e32 v87, s53
	v_lshlrev_b64 v[86:87], 11, v[86:87]
	s_waitcnt lgkmcnt(3)
	v_add_f32_e32 v78, 0, v78
	v_add_f32_e32 v78, v78, v79
	s_waitcnt lgkmcnt(2)
	v_add_f32_e32 v78, v78, v84
	v_add_f32_e32 v78, v78, v85
	s_waitcnt lgkmcnt(1)
	v_add_f32_e32 v78, v78, v88
	v_add_f32_e32 v78, v78, v89
	s_waitcnt lgkmcnt(0)
; #define LAS __attribute__((address_space(3)))
; DI unsigned pk2(float lo, float hi) { unsigned r; asm("v_cvt_pk_bf16_f32 %0, %1, %2" : "=v"(r) : "v"(lo), "v"(hi)); return r; }
; DI float bflo(unsigned u) { return __uint_as_float(u << 16); }
; DI float bfhi(unsigned u) { return __uint_as_float(u & 0xffff0000u); }
; DI float fsilu(float x) { return x * fsigmoid(x); }
; DI void ret_out_phase(int l, unsigned char* lds_g, LAS unsigned char* lds) {
;     ...
;         for (int nt = 0; nt < 8; ++nt) { const int i = 16 * nt + fr; float tot = 0.f;
; #pragma unroll
;             for (int ww = 0; ww < 8; ++ww) tot += *(const LAS float*)(lds + OT + (ww * 128 + i) * 4);
;             const float rinv = __builtin_amdgcn_rsqf(tot * (1.0f / 256.0f) + EPS);
; #pragma unroll
;             for (int m = 0; m < 2; ++m) { const int dv = h * 256 + 32 * w + 16 * m + 4 * fq;
;                 const u32x2 gz = *(const u32x2*)(Z + (row0 + i) * INW + ZC_RG + dv); const f32x4 gn = *(const f32x4*)(rn + dv);
;                 const float o0 = O[m][nt][0] * rinv * gn[0] * fsilu(bflo(gz.x)), o1 = O[m][nt][1] * rinv * gn[1] * fsilu(bfhi(gz.x));
;                 const float o2 = O[m][nt][2] * rinv * gn[2] * fsilu(bflo(gz.y)), o3 = O[m][nt][3] * rinv * gn[3] * fsilu(bfhi(gz.y));
;                 u32x2 o; o.x = pk2(o0, o1); o.y = pk2(o2, o3);
;                 *(u32x2*)(R + (row0 + i) * 1024 + dv) = o; }
;             asm volatile("" ::: "memory"); }
	v_add_f32_e32 v78, v78, v90
	v_add_f32_e32 v78, v78, v91
	v_fmamk_f32 v78, v78, 0x3b800000, v243
	v_rsq_f32_e32 v84, v78
	v_lshl_add_u64 v[78:79], s[48:49], 0, v[86:87]
	v_lshl_add_u64 v[78:79], v[78:79], 0, v[72:73]
	v_mul_f32_e32 v86, v18, v84
	v_mul_f32_e32 v88, v19, v84
	v_mul_f32_e32 v90, v20, v84
	v_mul_f32_e32 v92, v21, v84
	s_waitcnt vmcnt(15)
	v_mov_b32_e32 v82, v116
	v_mov_b32_e32 v83, v117
	v_lshlrev_b32_e32 v87, 16, v82
	v_and_b32_e32 v89, 0xffff0000, v82
	v_mov_b32_e32 v66, v200
	v_mov_b32_e32 v67, v201
	v_mov_b32_e32 v68, v202
	v_mov_b32_e32 v69, v203
	v_mov_b32_e32 v82, v67
	v_lshlrev_b32_e32 v91, 16, v83
	v_and_b32_e32 v93, 0xffff0000, v83
	v_mov_b32_e32 v94, v69
	v_mul_f32_e32 v67, 0xbfb8aa3b, v87
	v_mul_f32_e32 v69, 0xbfb8aa3b, v89
	v_mul_f32_e32 v83, 0xbfb8aa3b, v91
	v_mul_f32_e32 v85, 0xbfb8aa3b, v93
	v_exp_f32_e32 v67, v67
	v_exp_f32_e32 v69, v69
	v_exp_f32_e32 v83, v83
	v_exp_f32_e32 v85, v85
	v_add_f32_e32 v67, 1.0, v67
	v_add_f32_e32 v69, 1.0, v69
	v_add_f32_e32 v95, 1.0, v83
	v_add_f32_e32 v85, 1.0, v85
	v_rcp_f32_e32 v67, v67
	v_rcp_f32_e32 v83, v69
	v_rcp_f32_e32 v69, v95
	v_rcp_f32_e32 v95, v85
	v_pk_mul_f32 v[66:67], v[66:67], v[86:87]
	v_pk_mul_f32 v[82:83], v[82:83], v[88:89]
	v_pk_mul_f32 v[68:69], v[68:69], v[90:91]
	v_pk_mul_f32 v[86:87], v[94:95], v[92:93]
	v_mul_f32_e32 v66, v66, v67
	v_mul_f32_e32 v67, v82, v83
	v_mul_f32_e32 v68, v68, v69
	v_mul_f32_e32 v69, v86, v87
	v_cvt_pk_bf16_f32 v66, v66, v67
	v_cvt_pk_bf16_f32 v67, v68, v69
	global_store_dwordx2 v[78:79], v[66:67], off
	s_nop 0
	v_or_b32_e32 v86, s52, v168
	v_mul_f32_e32 v94, v52, v84
	v_mad_u64_u32 v[80:81], s[22:23], v86, s78, v[76:77]
	v_mul_f32_e32 v90, v50, v84
	v_mul_f32_e32 v92, v51, v84
	v_mul_f32_e32 v84, v53, v84
	v_add_u32_e32 v81, s7, v81
	v_lshl_add_u64 v[80:81], v[80:81], 0, s[28:29]
	v_lshl_add_u64 v[88:89], v[80:81], 0, v[72:73]
	v_lshl_add_u64 v[80:81], v[80:81], 0, v[74:75]
	s_waitcnt vmcnt(15)
	v_mov_b32_e32 v82, v118
	v_mov_b32_e32 v83, v119
	v_lshlrev_b32_e32 v97, 16, v82
	v_mov_b32_e32 v66, v224
	v_mov_b32_e32 v67, v225
	v_mov_b32_e32 v68, v226
	v_mov_b32_e32 v69, v227
	v_mov_b32_e32 v98, v67
	v_lshlrev_b32_e32 v67, 16, v83
	v_and_b32_e32 v99, 0xffff0000, v82
	v_and_b32_e32 v83, 0xffff0000, v83
	v_mul_f32_e32 v85, 0xbfb8aa3b, v67
	v_mov_b32_e32 v96, v66
	v_mov_b32_e32 v66, v68
	v_mov_b32_e32 v82, v69
	v_mul_f32_e32 v68, 0xbfb8aa3b, v97
	v_mul_f32_e32 v69, 0xbfb8aa3b, v99
	v_mul_f32_e32 v87, 0xbfb8aa3b, v83
	v_exp_f32_e32 v85, v85
	v_exp_f32_e32 v68, v68
	v_exp_f32_e32 v69, v69
	v_exp_f32_e32 v87, v87
	v_add_f32_e32 v85, 1.0, v85
	v_add_f32_e32 v68, 1.0, v68
	v_add_f32_e32 v69, 1.0, v69
	v_add_f32_e32 v87, 1.0, v87
	v_rcp_f32_e32 v95, v85
	v_rcp_f32_e32 v91, v68
	v_rcp_f32_e32 v93, v69
	v_rcp_f32_e32 v85, v87
	v_pk_mul_f32 v[66:67], v[94:95], v[66:67]
	v_pk_mul_f32 v[68:69], v[90:91], v[96:97]
	v_pk_mul_f32 v[90:91], v[92:93], v[98:99]
	v_pk_mul_f32 v[82:83], v[84:85], v[82:83]
	v_mul_f32_e32 v67, v66, v67
	v_mul_f32_e32 v68, v68, v69
	v_mul_f32_e32 v69, v90, v91
	v_mul_f32_e32 v82, v82, v83
	v_cvt_pk_bf16_f32 v66, v68, v69
	v_cvt_pk_bf16_f32 v67, v67, v82
	global_store_dwordx2 v[78:79], v[66:67], off offset:32
	ds_read2st64_b32 v[78:79], v216 offset1:2
	ds_read2st64_b32 v[84:85], v216 offset0:4 offset1:6
	ds_read2st64_b32 v[88:89], v216 offset0:8 offset1:10
	ds_read2st64_b32 v[90:91], v216 offset0:12 offset1:14
	v_mov_b32_e32 v87, s53
	v_lshlrev_b64 v[86:87], 11, v[86:87]
	s_waitcnt lgkmcnt(3)
	v_add_f32_e32 v78, 0, v78
	v_add_f32_e32 v78, v78, v79
	s_waitcnt lgkmcnt(2)
	v_add_f32_e32 v78, v78, v84
	v_add_f32_e32 v78, v78, v85
	s_waitcnt lgkmcnt(1)
	v_add_f32_e32 v78, v78, v88
	v_add_f32_e32 v78, v78, v89
	s_waitcnt lgkmcnt(0)
	v_add_f32_e32 v78, v78, v90
	v_add_f32_e32 v78, v78, v91
	v_fmamk_f32 v78, v78, 0x3b800000, v243
	v_rsq_f32_e32 v84, v78
	v_lshl_add_u64 v[78:79], s[48:49], 0, v[86:87]
	v_lshl_add_u64 v[78:79], v[78:79], 0, v[72:73]
	v_mul_f32_e32 v86, v22, v84
	v_mul_f32_e32 v88, v23, v84
	v_mul_f32_e32 v90, v24, v84
	v_mul_f32_e32 v92, v25, v84
	s_waitcnt vmcnt(15)
	v_mov_b32_e32 v82, v120
	v_mov_b32_e32 v83, v121
	v_lshlrev_b32_e32 v87, 16, v82
	v_and_b32_e32 v89, 0xffff0000, v82
	v_mov_b32_e32 v66, v200
	v_mov_b32_e32 v67, v201
	v_mov_b32_e32 v68, v202
	v_mov_b32_e32 v69, v203
	v_mov_b32_e32 v82, v67
	v_lshlrev_b32_e32 v91, 16, v83
	v_and_b32_e32 v93, 0xffff0000, v83
	v_mov_b32_e32 v94, v69
	v_mul_f32_e32 v67, 0xbfb8aa3b, v87
	v_mul_f32_e32 v69, 0xbfb8aa3b, v89
	v_mul_f32_e32 v83, 0xbfb8aa3b, v91
	v_mul_f32_e32 v85, 0xbfb8aa3b, v93
	v_exp_f32_e32 v67, v67
	v_exp_f32_e32 v69, v69
	v_exp_f32_e32 v83, v83
	v_exp_f32_e32 v85, v85
	v_add_f32_e32 v67, 1.0, v67
	v_add_f32_e32 v69, 1.0, v69
	v_add_f32_e32 v95, 1.0, v83
	v_add_f32_e32 v85, 1.0, v85
	v_rcp_f32_e32 v67, v67
	v_rcp_f32_e32 v83, v69
	v_rcp_f32_e32 v69, v95
	v_rcp_f32_e32 v95, v85
	v_pk_mul_f32 v[66:67], v[66:67], v[86:87]
	v_pk_mul_f32 v[82:83], v[82:83], v[88:89]
	v_pk_mul_f32 v[68:69], v[68:69], v[90:91]
	v_pk_mul_f32 v[86:87], v[94:95], v[92:93]
	v_mul_f32_e32 v66, v66, v67
	v_mul_f32_e32 v67, v82, v83
	v_mul_f32_e32 v68, v68, v69
	v_mul_f32_e32 v69, v86, v87
	v_cvt_pk_bf16_f32 v66, v66, v67
	v_cvt_pk_bf16_f32 v67, v68, v69
	global_store_dwordx2 v[78:79], v[66:67], off
	s_nop 0
	v_or_b32_e32 v86, s52, v170
	v_mul_f32_e32 v94, v56, v84
	v_mad_u64_u32 v[80:81], s[22:23], v86, s78, v[76:77]
	v_mul_f32_e32 v90, v54, v84
	v_mul_f32_e32 v92, v55, v84
	v_mul_f32_e32 v84, v57, v84
	v_add_u32_e32 v81, s7, v81
	v_lshl_add_u64 v[80:81], v[80:81], 0, s[28:29]
	v_lshl_add_u64 v[88:89], v[80:81], 0, v[72:73]
	v_lshl_add_u64 v[80:81], v[80:81], 0, v[74:75]
	s_waitcnt vmcnt(15)
; #define LAS __attribute__((address_space(3)))
; DI unsigned pk2(float lo, float hi) { unsigned r; asm("v_cvt_pk_bf16_f32 %0, %1, %2" : "=v"(r) : "v"(lo), "v"(hi)); return r; }
; DI float bflo(unsigned u) { return __uint_as_float(u << 16); }
; DI float bfhi(unsigned u) { return __uint_as_float(u & 0xffff0000u); }
; DI float fsilu(float x) { return x * fsigmoid(x); }
; DI void ret_out_phase(int l, unsigned char* lds_g, LAS unsigned char* lds) {
;     ...
;         for (int nt = 0; nt < 8; ++nt) { const int i = 16 * nt + fr; float tot = 0.f;
; #pragma unroll
;             for (int ww = 0; ww < 8; ++ww) tot += *(const LAS float*)(lds + OT + (ww * 128 + i) * 4);
;             const float rinv = __builtin_amdgcn_rsqf(tot * (1.0f / 256.0f) + EPS);
; #pragma unroll
;             for (int m = 0; m < 2; ++m) { const int dv = h * 256 + 32 * w + 16 * m + 4 * fq;
;                 const u32x2 gz = *(const u32x2*)(Z + (row0 + i) * INW + ZC_RG + dv); const f32x4 gn = *(const f32x4*)(rn + dv);
;                 const float o0 = O[m][nt][0] * rinv * gn[0] * fsilu(bflo(gz.x)), o1 = O[m][nt][1] * rinv * gn[1] * fsilu(bfhi(gz.x));
;                 const float o2 = O[m][nt][2] * rinv * gn[2] * fsilu(bflo(gz.y)), o3 = O[m][nt][3] * rinv * gn[3] * fsilu(bfhi(gz.y));
;                 u32x2 o; o.x = pk2(o0, o1); o.y = pk2(o2, o3);
;                 *(u32x2*)(R + (row0 + i) * 1024 + dv) = o; }
;             asm volatile("" ::: "memory"); }
	v_mov_b32_e32 v82, v122
	v_mov_b32_e32 v83, v123
	v_lshlrev_b32_e32 v97, 16, v82
	v_mov_b32_e32 v66, v224
	v_mov_b32_e32 v67, v225
	v_mov_b32_e32 v68, v226
	v_mov_b32_e32 v69, v227
	v_mov_b32_e32 v98, v67
	v_lshlrev_b32_e32 v67, 16, v83
	v_and_b32_e32 v99, 0xffff0000, v82
	v_and_b32_e32 v83, 0xffff0000, v83
	v_mul_f32_e32 v85, 0xbfb8aa3b, v67
	v_mov_b32_e32 v96, v66
	v_mov_b32_e32 v66, v68
	v_mov_b32_e32 v82, v69
	v_mul_f32_e32 v68, 0xbfb8aa3b, v97
	v_mul_f32_e32 v69, 0xbfb8aa3b, v99
	v_mul_f32_e32 v87, 0xbfb8aa3b, v83
	v_exp_f32_e32 v85, v85
	v_exp_f32_e32 v68, v68
	v_exp_f32_e32 v69, v69
	v_exp_f32_e32 v87, v87
	v_add_f32_e32 v85, 1.0, v85
	v_add_f32_e32 v68, 1.0, v68
	v_add_f32_e32 v69, 1.0, v69
	v_add_f32_e32 v87, 1.0, v87
	v_rcp_f32_e32 v95, v85
	v_rcp_f32_e32 v91, v68
	v_rcp_f32_e32 v93, v69
	v_rcp_f32_e32 v85, v87
	v_pk_mul_f32 v[66:67], v[94:95], v[66:67]
	v_pk_mul_f32 v[68:69], v[90:91], v[96:97]
	v_pk_mul_f32 v[90:91], v[92:93], v[98:99]
	v_pk_mul_f32 v[82:83], v[84:85], v[82:83]
	v_mul_f32_e32 v67, v66, v67
	v_mul_f32_e32 v68, v68, v69
	v_mul_f32_e32 v69, v90, v91
	v_mul_f32_e32 v82, v82, v83
	v_cvt_pk_bf16_f32 v66, v68, v69
	v_cvt_pk_bf16_f32 v67, v67, v82
	global_store_dwordx2 v[78:79], v[66:67], off offset:32
	ds_read2st64_b32 v[78:79], v217 offset1:2
	ds_read2st64_b32 v[82:83], v217 offset0:4 offset1:6
	ds_read2st64_b32 v[88:89], v217 offset0:8 offset1:10
	ds_read2st64_b32 v[90:91], v217 offset0:12 offset1:14
	v_mov_b32_e32 v87, s53
	v_lshlrev_b64 v[86:87], 11, v[86:87]
	s_waitcnt lgkmcnt(3)
	v_add_f32_e32 v78, 0, v78
	v_add_f32_e32 v78, v78, v79
	s_waitcnt lgkmcnt(2)
	v_add_f32_e32 v78, v78, v82
	v_add_f32_e32 v78, v78, v83
	s_waitcnt lgkmcnt(1)
	v_add_f32_e32 v78, v78, v88
	v_add_f32_e32 v78, v78, v89
	s_waitcnt lgkmcnt(0)
	v_add_f32_e32 v78, v78, v90
	v_add_f32_e32 v78, v78, v91
	v_fmamk_f32 v78, v78, 0x3b800000, v243
	v_rsq_f32_e32 v82, v78
	v_lshl_add_u64 v[78:79], s[48:49], 0, v[86:87]
	v_lshl_add_u64 v[78:79], v[78:79], 0, v[72:73]
	v_mul_f32_e32 v86, v26, v82
	v_mul_f32_e32 v88, v27, v82
	v_mul_f32_e32 v90, v28, v82
	v_mul_f32_e32 v92, v29, v82
	s_waitcnt vmcnt(15)
	v_mov_b32_e32 v84, v124
	v_mov_b32_e32 v85, v125
	v_lshlrev_b32_e32 v87, 16, v84
	v_and_b32_e32 v89, 0xffff0000, v84
	v_mov_b32_e32 v66, v200
	v_mov_b32_e32 v67, v201
	v_mov_b32_e32 v68, v202
	v_mov_b32_e32 v69, v203
	v_mov_b32_e32 v84, v67
	v_lshlrev_b32_e32 v91, 16, v85
	v_and_b32_e32 v93, 0xffff0000, v85
	v_mov_b32_e32 v94, v69
	v_mul_f32_e32 v67, 0xbfb8aa3b, v87
	v_mul_f32_e32 v69, 0xbfb8aa3b, v89
	v_mul_f32_e32 v83, 0xbfb8aa3b, v91
	v_mul_f32_e32 v85, 0xbfb8aa3b, v93
	v_exp_f32_e32 v67, v67
	v_exp_f32_e32 v69, v69
	v_exp_f32_e32 v83, v83
	v_exp_f32_e32 v85, v85
	v_add_f32_e32 v67, 1.0, v67
	v_add_f32_e32 v69, 1.0, v69
	v_add_f32_e32 v83, 1.0, v83
	v_add_f32_e32 v95, 1.0, v85
	v_rcp_f32_e32 v67, v67
	v_rcp_f32_e32 v85, v69
	v_rcp_f32_e32 v69, v83
	v_rcp_f32_e32 v95, v95
	v_pk_mul_f32 v[66:67], v[66:67], v[86:87]
	v_pk_mul_f32 v[84:85], v[84:85], v[88:89]
	v_pk_mul_f32 v[68:69], v[68:69], v[90:91]
	v_pk_mul_f32 v[86:87], v[94:95], v[92:93]
	v_mul_f32_e32 v66, v66, v67
	v_mul_f32_e32 v67, v84, v85
	v_mul_f32_e32 v68, v68, v69
	v_mul_f32_e32 v69, v86, v87
	v_cvt_pk_bf16_f32 v66, v66, v67
	v_cvt_pk_bf16_f32 v67, v68, v69
	global_store_dwordx2 v[78:79], v[66:67], off
	s_nop 0
	v_or_b32_e32 v84, s52, v172
	v_mul_f32_e32 v92, v60, v82
	v_mad_u64_u32 v[76:77], s[22:23], v84, s78, v[76:77]
	v_mul_f32_e32 v88, v58, v82
	v_mul_f32_e32 v90, v59, v82
	v_mul_f32_e32 v82, v61, v82
	v_add_u32_e32 v77, s7, v77
	v_lshl_add_u64 v[76:77], v[76:77], 0, s[28:29]
	v_lshl_add_u64 v[86:87], v[76:77], 0, v[72:73]
	v_lshl_add_u64 v[74:75], v[76:77], 0, v[74:75]
	s_waitcnt vmcnt(15)
; #define LAS __attribute__((address_space(3)))
; DI unsigned pk2(float lo, float hi) { unsigned r; asm("v_cvt_pk_bf16_f32 %0, %1, %2" : "=v"(r) : "v"(lo), "v"(hi)); return r; }
; DI float bflo(unsigned u) { return __uint_as_float(u << 16); }
; DI float bfhi(unsigned u) { return __uint_as_float(u & 0xffff0000u); }
; DI float fsilu(float x) { return x * fsigmoid(x); }
; DI void ret_out_phase(int l, unsigned char* lds_g, LAS unsigned char* lds) {
;     ...
;         for (int nt = 0; nt < 8; ++nt) { const int i = 16 * nt + fr; float tot = 0.f;
; #pragma unroll
;             for (int ww = 0; ww < 8; ++ww) tot += *(const LAS float*)(lds + OT + (ww * 128 + i) * 4);
;             const float rinv = __builtin_amdgcn_rsqf(tot * (1.0f / 256.0f) + EPS);
; #pragma unroll
;             for (int m = 0; m < 2; ++m) { const int dv = h * 256 + 32 * w + 16 * m + 4 * fq;
;                 const u32x2 gz = *(const u32x2*)(Z + (row0 + i) * INW + ZC_RG + dv); const f32x4 gn = *(const f32x4*)(rn + dv);
;                 const float o0 = O[m][nt][0] * rinv * gn[0] * fsilu(bflo(gz.x)), o1 = O[m][nt][1] * rinv * gn[1] * fsilu(bfhi(gz.x));
;                 const float o2 = O[m][nt][2] * rinv * gn[2] * fsilu(bflo(gz.y)), o3 = O[m][nt][3] * rinv * gn[3] * fsilu(bfhi(gz.y));
;                 u32x2 o; o.x = pk2(o0, o1); o.y = pk2(o2, o3);
;                 *(u32x2*)(R + (row0 + i) * 1024 + dv) = o; }
;             asm volatile("" ::: "memory"); }
;         __syncthreads();
	v_mov_b32_e32 v80, v126
	v_mov_b32_e32 v81, v127
	v_lshlrev_b32_e32 v95, 16, v80
	v_mov_b32_e32 v66, v224
	v_mov_b32_e32 v67, v225
	v_mov_b32_e32 v68, v226
	v_mov_b32_e32 v69, v227
	v_mov_b32_e32 v96, v67
	v_lshlrev_b32_e32 v67, 16, v81
	v_and_b32_e32 v97, 0xffff0000, v80
	v_and_b32_e32 v81, 0xffff0000, v81
	v_mul_f32_e32 v83, 0xbfb8aa3b, v67
	v_mov_b32_e32 v94, v66
	v_mov_b32_e32 v66, v68
	v_mov_b32_e32 v80, v69
	v_mul_f32_e32 v68, 0xbfb8aa3b, v95
	v_mul_f32_e32 v69, 0xbfb8aa3b, v97
	v_mul_f32_e32 v85, 0xbfb8aa3b, v81
	v_exp_f32_e32 v83, v83
	v_exp_f32_e32 v68, v68
	v_exp_f32_e32 v69, v69
	v_exp_f32_e32 v85, v85
	v_add_f32_e32 v83, 1.0, v83
	v_add_f32_e32 v68, 1.0, v68
	v_add_f32_e32 v69, 1.0, v69
	v_add_f32_e32 v85, 1.0, v85
	v_rcp_f32_e32 v93, v83
	v_rcp_f32_e32 v89, v68
	v_rcp_f32_e32 v91, v69
	v_rcp_f32_e32 v83, v85
	v_pk_mul_f32 v[66:67], v[92:93], v[66:67]
	v_pk_mul_f32 v[68:69], v[88:89], v[94:95]
	v_pk_mul_f32 v[88:89], v[90:91], v[96:97]
	v_pk_mul_f32 v[80:81], v[82:83], v[80:81]
	v_mul_f32_e32 v67, v66, v67
	v_mul_f32_e32 v68, v68, v69
	v_mul_f32_e32 v69, v88, v89
	v_mul_f32_e32 v80, v80, v81
	v_cvt_pk_bf16_f32 v66, v68, v69
	v_cvt_pk_bf16_f32 v67, v67, v80
	global_store_dwordx2 v[78:79], v[66:67], off offset:32
	ds_read2st64_b32 v[80:81], v218 offset1:2
	v_mov_b32_e32 v85, s53
	v_lshlrev_b64 v[82:83], 11, v[84:85]
	ds_read2st64_b32 v[84:85], v218 offset0:4 offset1:6
	ds_read2st64_b32 v[86:87], v218 offset0:8 offset1:10
	ds_read2st64_b32 v[88:89], v218 offset0:12 offset1:14
	s_waitcnt lgkmcnt(3)
	v_add_f32_e32 v80, 0, v80
	v_add_f32_e32 v80, v80, v81
	s_waitcnt lgkmcnt(2)
	v_add_f32_e32 v80, v80, v84
	v_add_f32_e32 v80, v80, v85
	s_waitcnt lgkmcnt(1)
	v_add_f32_e32 v80, v80, v86
	v_add_f32_e32 v80, v80, v87
	s_waitcnt lgkmcnt(0)
	v_add_f32_e32 v80, v80, v88
	v_add_f32_e32 v80, v80, v89
	v_fmamk_f32 v80, v80, 0x3b800000, v243
	v_rsq_f32_e32 v88, v80
	v_lshl_add_u64 v[80:81], s[48:49], 0, v[82:83]
	v_lshl_add_u64 v[72:73], v[80:81], 0, v[72:73]
	v_mul_f32_e32 v76, v30, v88
	v_mul_f32_e32 v80, v31, v88
	v_mul_f32_e32 v82, v32, v88
	v_mul_f32_e32 v84, v33, v88
	s_waitcnt vmcnt(15)
	v_mov_b32_e32 v78, v220
	v_mov_b32_e32 v79, v221
	v_lshlrev_b32_e32 v77, 16, v78
	v_and_b32_e32 v81, 0xffff0000, v78
	v_mov_b32_e32 v66, v200
	v_mov_b32_e32 v67, v201
	v_mov_b32_e32 v68, v202
	v_mov_b32_e32 v69, v203
	v_mov_b32_e32 v78, v67
	v_lshlrev_b32_e32 v83, 16, v79
	v_and_b32_e32 v85, 0xffff0000, v79
	v_mov_b32_e32 v86, v69
	v_mul_f32_e32 v67, 0xbfb8aa3b, v77
	v_mul_f32_e32 v69, 0xbfb8aa3b, v81
	v_mul_f32_e32 v79, 0xbfb8aa3b, v83
	v_mul_f32_e32 v87, 0xbfb8aa3b, v85
	v_exp_f32_e32 v67, v67
	v_exp_f32_e32 v69, v69
	v_exp_f32_e32 v79, v79
	v_exp_f32_e32 v87, v87
	v_add_f32_e32 v67, 1.0, v67
	v_add_f32_e32 v69, 1.0, v69
	v_add_f32_e32 v89, 1.0, v79
	v_add_f32_e32 v87, 1.0, v87
	v_rcp_f32_e32 v67, v67
	v_rcp_f32_e32 v79, v69
	v_rcp_f32_e32 v69, v89
	v_rcp_f32_e32 v87, v87
	v_pk_mul_f32 v[66:67], v[66:67], v[76:77]
	v_pk_mul_f32 v[76:77], v[78:79], v[80:81]
	v_pk_mul_f32 v[68:69], v[68:69], v[82:83]
	v_pk_mul_f32 v[78:79], v[86:87], v[84:85]
	v_mul_f32_e32 v66, v66, v67
	v_mul_f32_e32 v67, v76, v77
	v_mul_f32_e32 v68, v68, v69
	v_mul_f32_e32 v69, v78, v79
	v_cvt_pk_bf16_f32 v66, v66, v67
	v_cvt_pk_bf16_f32 v67, v68, v69
	global_store_dwordx2 v[72:73], v[66:67], off
	s_nop 0
	v_mul_f32_e32 v78, v64, v88
	v_mul_f32_e32 v70, v62, v88
	v_mul_f32_e32 v76, v63, v88
	v_mul_f32_e32 v80, v65, v88
	s_waitcnt vmcnt(15)
	v_mov_b32_e32 v74, v222
	v_mov_b32_e32 v75, v223
	v_lshlrev_b32_e32 v83, 16, v74
	v_mov_b32_e32 v66, v224
	v_mov_b32_e32 v67, v225
	v_mov_b32_e32 v68, v226
	v_mov_b32_e32 v69, v227
	v_mov_b32_e32 v84, v67
	v_lshlrev_b32_e32 v67, 16, v75
	v_and_b32_e32 v85, 0xffff0000, v74
	v_and_b32_e32 v75, 0xffff0000, v75
	v_mul_f32_e32 v71, 0xbfb8aa3b, v67
	v_mov_b32_e32 v82, v66
	v_mov_b32_e32 v66, v68
	v_mov_b32_e32 v74, v69
	v_mul_f32_e32 v68, 0xbfb8aa3b, v83
	v_mul_f32_e32 v69, 0xbfb8aa3b, v85
	v_mul_f32_e32 v77, 0xbfb8aa3b, v75
	v_exp_f32_e32 v71, v71
	v_exp_f32_e32 v68, v68
	v_exp_f32_e32 v69, v69
	v_exp_f32_e32 v77, v77
	v_add_f32_e32 v79, 1.0, v71
	v_add_f32_e32 v68, 1.0, v68
	v_add_f32_e32 v69, 1.0, v69
	v_add_f32_e32 v81, 1.0, v77
	v_rcp_f32_e32 v79, v79
	v_rcp_f32_e32 v71, v68
	v_rcp_f32_e32 v77, v69
	v_rcp_f32_e32 v81, v81
	v_pk_mul_f32 v[66:67], v[78:79], v[66:67]
	v_pk_mul_f32 v[68:69], v[70:71], v[82:83]
	v_pk_mul_f32 v[70:71], v[76:77], v[84:85]
	v_pk_mul_f32 v[74:75], v[80:81], v[74:75]
	v_mul_f32_e32 v67, v66, v67
	v_mul_f32_e32 v68, v68, v69
	v_mul_f32_e32 v69, v70, v71
	v_mul_f32_e32 v70, v74, v75
	v_cvt_pk_bf16_f32 v66, v68, v69
	v_cvt_pk_bf16_f32 v67, v67, v70
	global_store_dwordx2 v[72:73], v[66:67], off offset:32
	s_barrier
	s_cbranch_scc0 .LBB0_446
